# attention: static s_setprio 1 for waves 4-7 during the attention phase, on top of one barrier per KV tile
# baseline (speedup 1.0000x reference)
; #define VMW() asm volatile("s_waitcnt vmcnt(0)" ::: "memory")
; #define SLOAD_H(Kp, Vp, k0) do { S.st_v0 = load8(VROW(Vp, k0, sr)); S.st_v1 = load8(VROW(Vp, k0, 32 + sr));              \
;                          S.st_k0 = load8(KROW(Kp, k0)); S.st_k1 = load8(KROW(Kp, k0) + 64); S.st_k2 = load8(KROW(Kp, k0) + 128); } while (0)
; #define SWRITE_HK(bf) do { *(bf16x8*)(K_lds + (bf) * SHM_K + kws) = S.st_k0; *(bf16x8*)(K_lds + (bf) * SHM_K + kws + 128) = S.st_k1; *(bf16x8*)(K_lds + (bf) * SHM_K + kws + 256) = S.st_k2; } while (0)
; __device__ __forceinline__ void attn_prime(const BlockRef& cur, int W, char* lds, Seam& S) {
;     int tid_ = threadIdx.x; asm volatile("" : "+v"(tid_));
;     const int tid = tid_, wid = __builtin_amdgcn_readfirstlane(tid >> 6), lane = tid & 63, r32 = lane & 31, hi = lane >> 5;
;     const int sr = tid >> 4, sc = (tid & 15) * 8, kr_ = tid >> 3, kc_ = (tid & 7) * 8, kws = KSWZ(kr_, kc_ * 2); char* K_lds = lds + 2 * SHM_V;
;     const int kb0 = swa_jlo(cur.P0, W) * KVBLK;
; #pragma unroll
;     for (int d0 = 0; d0 < NQR; ++d0) S.qr[d0] = load8(cur.Q + (size_t)(wid * QBLK + r32) * QS + d0 * 16 + hi * 8);
; #pragma unroll
;     for (int d0 = 0; d0 < NQL_; ++d0) S.qt[d0] = load8(cur.Q + (size_t)(wid * QBLK + r32) * QS + (NQR + d0) * 16 + hi * 8);
;     SLOAD_H(cur.K, cur.V, kb0); VMW(); SWRITE_HK(0);
;     __syncthreads();
; }
; __device__ __forceinline__ void attn_phase(char* lds, const bf16* Q, const bf16* K, const bf16* V, bf16* O, int vcu, int G) {
;     constexpr int NQB = SEQ / QB, NX = NQB / 2, TOTAL = 2 * NH * NX;
;     int L = vcu; if (L >= TOTAL) return;
;     int bh = L / NX, x = L % NX, pass = 0;
;     BlockRef cur = blk_ref(bh, x, Q, K, V, O);
;     Seam S;
;     attn_prime(cur, SEQ, lds, S);
.LBB0_517:
	s_or_b64 exec, exec, s[0:1]
	s_cmpk_gt_i32 s95, 0xff
	s_waitcnt lgkmcnt(0)
	s_barrier
	s_cbranch_scc1 .LBB0_563
	v_readfirstlane_b32 s100, v226
	s_nop 0
	s_cmp_lt_u32 s100, 0x100
	s_cbranch_scc1 .Latt_prio_skip
	s_setprio 1
.Latt_prio_skip:
	s_ashr_i32 s0, s95, 31
	s_lshr_b32 s1, s0, 29
	s_add_i32 s1, s95, s1
	s_ashr_i32 s13, s1, 3
	s_and_b32 s1, s1, -8
	s_sub_i32 s8, s95, s1
	s_lshr_b32 s0, s0, 25
	s_lshr_b32 s1, s13, 28
	s_add_i32 s0, s95, s0
	s_add_i32 s1, s13, s1
	s_ashr_i32 s0, s0, 7
	s_and_b32 s1, s1, -16
	s_sub_i32 s3, s13, s1
	s_ashr_i32 s1, s0, 31
	s_ashr_i32 s9, s8, 31
	s_lshl_b64 s[4:5], s[0:1], 12
	s_lshl_b64 s[10:11], s[8:9], 8
	s_add_u32 s4, s4, s10
	s_addc_u32 s5, s5, s11
	s_mul_i32 s10, s5, 0x1800
	s_mul_hi_u32 s11, s4, 0x1800
	s_add_i32 s11, s11, s10
	s_mul_i32 s10, s4, 0x1800
	s_add_u32 s22, s16, s10
	s_mul_i32 s10, s3, 0xc0
	s_addc_u32 s23, s17, s11
	s_ashr_i32 s11, s10, 31
	s_lshl_b64 s[18:19], s[10:11], 1
	s_add_u32 s10, s22, s18
	s_addc_u32 s11, s23, s19
	s_lshl_b64 s[4:5], s[4:5], 12
	s_add_u32 s22, s14, s4
	s_addc_u32 s23, s15, s5
	s_lshl_b32 s4, s3, 7
	s_ashr_i32 s5, s4, 31
	s_lshl_b64 s[4:5], s[4:5], 1
	s_add_u32 s44, s22, s4
	s_addc_u32 s45, s23, s5
	s_mul_i32 s5, s0, 0x1800000
	s_mul_hi_i32 s4, s0, 0x1800000
	s_add_u32 s5, s6, s5
	s_addc_u32 s4, s7, s4
	s_add_u32 s48, s5, s18
	s_addc_u32 s49, s4, s19
	s_lshl_b64 s[0:1], s[0:1], 25
	s_add_u32 s4, s38, s0
	s_addc_u32 s5, s39, s1
	s_lshl_b32 s0, s3, 8
	s_ashr_i32 s1, s0, 31
	s_lshl_b64 s[0:1], s[0:1], 1
	s_add_u32 s0, s4, s0
	s_addc_u32 s1, s5, s1
	v_mov_b32_e32 v6, v226
	s_add_u32 s54, s0, 0x100
	s_addc_u32 s55, s1, 0
	v_readfirstlane_b32 s3, v6
	s_ashr_i32 s3, s3, 1
	s_movk_i32 s4, 0xffe0
	v_mov_b32_e32 v0, s3
	s_movk_i32 s9, 0x1800
	v_bfi_b32 v2, s4, v0, v6
	v_mov_b64_e32 v[0:1], s[10:11]
	v_mad_i64_i32 v[0:1], s[4:5], v2, s9, v[0:1]
	v_lshrrev_b32_e32 v2, 1, v6
	v_mov_b32_e32 v189, 0
	v_ashrrev_i32_e32 v7, 3, v6
	v_lshlrev_b32_e32 v8, 4, v6
	v_mov_b64_e32 v[4:5], s[48:49]
	v_and_b32_e32 v188, 16, v2
	v_and_b32_e32 v2, 0x70, v8
	v_mad_i64_i32 v[4:5], s[4:5], v7, s9, v[4:5]
	v_mov_b32_e32 v3, v189
	v_lshl_add_u64 v[0:1], v[0:1], 0, v[188:189]
	v_lshl_add_u64 v[2:3], v[4:5], 0, v[2:3]
	global_load_dwordx4 v[148:151], v[0:1], off
	global_load_dwordx4 v[144:147], v[0:1], off offset:32
	global_load_dwordx4 v[140:143], v[0:1], off offset:64
	global_load_dwordx4 v[136:139], v[0:1], off offset:96
	global_load_dwordx4 v[132:135], v[0:1], off offset:128
	global_load_dwordx4 v[128:131], v[0:1], off offset:160
	global_load_dwordx4 v[96:99], v[2:3], off
	global_load_dwordx4 v[100:103], v[2:3], off offset:128
	global_load_dwordx4 v[104:107], v[2:3], off offset:256
	global_load_dwordx4 v[116:119], v[0:1], off offset:192
	global_load_dwordx4 v[120:123], v[0:1], off offset:224
	global_load_dwordx4 v[124:127], v[0:1], off offset:256
	global_load_dwordx4 v[152:155], v[0:1], off offset:288
	global_load_dwordx4 v[156:159], v[0:1], off offset:320
	global_load_dwordx4 v[160:163], v[0:1], off offset:352
	v_ashrrev_i32_e32 v0, 4, v6
	v_ashrrev_i32_e32 v1, 31, v0
	v_lshlrev_b64 v[0:1], 13, v[0:1]
	v_lshl_add_u64 v[0:1], s[0:1], 0, v[0:1]
	v_and_b32_e32 v188, 0xf0, v8
	v_lshl_add_u64 v[0:1], v[0:1], 0, v[188:189]
	s_mov_b32 s0, 0x40000
	v_add_co_u32_e32 v2, vcc, s0, v0
	s_movk_i32 s19, 0x180
	s_nop 0
	v_addc_co_u32_e32 v3, vcc, 0, v1, vcc
	global_load_dwordx4 v[108:111], v[0:1], off offset:256
	global_load_dwordx4 v[112:115], v[2:3], off offset:256
	s_movk_i32 s24, 0x70
	s_waitcnt vmcnt(0)
	v_mul_lo_u32 v0, v7, s19
	v_bitop3_b32 v1, v8, v6, s24 bitop3:0x28
	s_lshl_b32 s35, s8, 8
	s_mov_b32 s65, 0
	v_add3_u32 v0, 0, v0, v1
	s_movk_i32 s25, 0x60
	s_movk_i32 s33, 0x1000
	s_movk_i32 s56, 0xefff
	s_mov_b32 s57, 0x41000000
	s_mov_b32 s18, 0x3dd53b94
	s_movk_i32 s58, 0x2000
	s_mov_b32 s59, 0x8000
	s_mov_b32 s60, 0xa000
	s_mov_b32 s61, 0x10000
	s_mov_b32 s62, 0x12000
	s_mov_b32 s63, 0x18000
	s_mov_b32 s64, 0x1a000
	v_mov_b32_e32 v198, 0xff800000
	v_mov_b32_e32 v199, 0xf149f2ca
	s_waitcnt vmcnt(10)
	ds_write_b128 v0, v[96:99] offset:32768
	s_waitcnt vmcnt(9)
	ds_write_b128 v0, v[100:103] offset:32896
	s_waitcnt vmcnt(8)
	ds_write_b128 v0, v[104:107] offset:33024
	s_waitcnt lgkmcnt(0)
	s_barrier
	s_branch .LBB0_520

; __device__ __forceinline__ unsigned xb_add(unsigned* p, unsigned v) { return __hip_atomic_fetch_add(p, v, __ATOMIC_RELAXED, __HIP_MEMORY_SCOPE_AGENT); }
; __device__ __forceinline__ void xcd_barrier(const XcdBarrier& b) {
;     asm volatile("s_waitcnt vmcnt(0)" ::: "memory");
;     __syncthreads();
;     if (threadIdx.x == 0) {
;         unsigned* bar = b.bar;
;         __builtin_amdgcn_s_waitcnt(0);
;         unsigned nloc = b.st[0], nx = b.st[1];
;         if (nloc == 0u) { xcd_barrier_complete(bar, b.x, nloc, nx); b.st[0] = nloc; b.st[1] = nx; }
;         const unsigned old = xb_add(&bar[XB_XSUB(b.x)], 1u);
.LBB0_563:
	s_setprio 0
	s_waitcnt vmcnt(0)
	s_barrier
	s_mov_b64 s[0:1], exec
	v_readlane_b32 s4, v254, 9
	v_readlane_b32 s5, v254, 10
	s_and_b64 s[4:5], s[0:1], s[4:5]
	s_mov_b64 exec, s[4:5]
	s_cbranch_execz .LBB0_613
	s_add_i32 s3, 0, 0x23fc0
	v_mov_b32_e32 v0, s3
	s_waitcnt vmcnt(0) expcnt(0) lgkmcnt(0)
	buffer_inv sc1
	ds_read_b32 v2, v0
	s_add_i32 s3, 0, 0x23fc4
	v_mov_b32_e32 v0, s3
	ds_read_b32 v0, v0
	s_waitcnt lgkmcnt(1)
	v_cmp_ne_u32_e32 vcc, 0, v2
	s_cbranch_vccnz .LBB0_579
	s_add_u32 s4, s30, 0x1000
	s_addc_u32 s5, s31, 0
	s_add_u32 s6, s30, 0x1100
	s_addc_u32 s7, s31, 0
	s_add_u32 s8, s30, 0x1200
	v_readlane_b32 s3, v254, 8
	s_addc_u32 s9, s31, 0
	s_mul_i32 s3, s87, s3
	s_add_u32 s10, s30, 0x1300
	s_mul_i32 s3, s3, s86
	s_addc_u32 s11, s31, 0
	s_mov_b32 s13, 1
	v_mov_b32_e32 v16, 0
	s_branch .LBB0_567
